# v15 + hot loop heads (5 GEMM mainloops, attention tile loop) aligned to 64-byte boundaries
# speedup vs baseline: 1.0081x; 1.0081x over previous
;     __host__ __device__ bool next(int i, Unit& u) const { if (!so.next(i >> 1, u)) return false; u.seg = i & 1; return true; }
; template <class Epi, class Sched, bool ALIGN_EPI = false, bool SP2 = false>
; __device__ __forceinline__ void gemm_phase(PG8_LAS unsigned char* lds, const Gemm g, const Sched& S, const Epi& E) {
;     ...
;         const bool has_next = S.next(ui + 1, nxt);
;         const char* nA = has_next ? (const char*)(nxt.seg ? g.A1 : g.A0) + (size_t)nxt.pm * tstep : cA; const char* nB = has_next ? (const char*)(nxt.seg ? g.B1 : g.B0) + (size_t)nxt.pn * tstep : cB;
;     ...
;         if (!(Epi::KEEP && cur.seg == 0)) {
; #pragma unroll
;         for (int a = 0; a < 2; ++a)
; #pragma unroll
;             for (int b = 0; b < 2; ++b)
; #pragma unroll
;                 for (int m = 0; m < 4; ++m)
; #pragma unroll
;                     for (int n = 0; n < 2; ++n) acc[a][b][m][n] = (f32x4){0.f, 0.f, 0.f, 0.f};
;         }
;         cur = nxt; cA = nA; cB = nB; ++ui;
.LBB0_342:
	s_ashr_i32 s53, s52, 31
	s_lshl_b64 s[30:31], s[52:53], 19
	s_add_u32 s74, s10, s30
	s_addc_u32 s75, s11, s31
	s_and_b64 s[30:31], s[4:5], exec
	s_cselect_b32 s53, s75, s79
	s_cselect_b32 vcc_lo, s74, s78
	s_ashr_i32 s55, s54, 31
	s_lshl_b64 s[30:31], s[54:55], 19
	s_add_u32 s76, s72, s30
	s_addc_u32 s77, s73, s31
	s_and_b64 s[30:31], s[4:5], exec
	s_cselect_b32 s55, s77, s81
	s_cselect_b32 vcc_hi, s76, s80
	s_add_u32 s78, s78, 0x40080
	s_addc_u32 s79, s79, 0
	s_add_u32 s84, s80, 0x100
	v_mov_b32_e32 v0, 0
	s_addc_u32 s3, s81, 0
	s_mov_b32 s30, -2
	v_mov_b32_e32 v1, v0
	v_mov_b32_e32 v2, v0
	v_mov_b32_e32 v3, v0
	v_mov_b32_e32 v4, v0
	v_mov_b32_e32 v5, v0
	v_mov_b32_e32 v6, v0
	v_mov_b32_e32 v7, v0
	v_mov_b32_e32 v8, v0
	v_mov_b32_e32 v9, v0
	v_mov_b32_e32 v10, v0
	v_mov_b32_e32 v11, v0
	v_mov_b32_e32 v12, v0
	v_mov_b32_e32 v13, v0
	v_mov_b32_e32 v14, v0
	v_mov_b32_e32 v15, v0
	v_mov_b32_e32 v24, v0
	v_mov_b32_e32 v25, v0
	v_mov_b32_e32 v26, v0
	v_mov_b32_e32 v27, v0
	v_mov_b32_e32 v28, v0
	v_mov_b32_e32 v29, v0
	v_mov_b32_e32 v30, v0
	v_mov_b32_e32 v31, v0
	v_mov_b32_e32 v40, v0
	v_mov_b32_e32 v41, v0
	v_mov_b32_e32 v42, v0
	v_mov_b32_e32 v43, v0
	v_mov_b32_e32 v44, v0
	v_mov_b32_e32 v45, v0
	v_mov_b32_e32 v46, v0
	v_mov_b32_e32 v47, v0
	v_mov_b32_e32 v16, v0
	v_mov_b32_e32 v17, v0
	v_mov_b32_e32 v18, v0
	v_mov_b32_e32 v19, v0
	v_mov_b32_e32 v20, v0
	v_mov_b32_e32 v21, v0
	v_mov_b32_e32 v22, v0
	v_mov_b32_e32 v23, v0
	v_mov_b32_e32 v32, v0
	v_mov_b32_e32 v33, v0
	v_mov_b32_e32 v34, v0
	v_mov_b32_e32 v35, v0
	v_mov_b32_e32 v36, v0
	v_mov_b32_e32 v37, v0
	v_mov_b32_e32 v38, v0
	v_mov_b32_e32 v39, v0
	v_mov_b32_e32 v48, v0
	v_mov_b32_e32 v49, v0
	v_mov_b32_e32 v50, v0
	v_mov_b32_e32 v51, v0
	v_mov_b32_e32 v52, v0
	v_mov_b32_e32 v53, v0
	v_mov_b32_e32 v54, v0
	v_mov_b32_e32 v55, v0
	v_mov_b32_e32 v56, v0
	v_mov_b32_e32 v57, v0
	v_mov_b32_e32 v58, v0
	v_mov_b32_e32 v59, v0
	v_mov_b32_e32 v60, v0
	v_mov_b32_e32 v61, v0
	v_mov_b32_e32 v62, v0
	v_mov_b32_e32 v63, v0
	v_mov_b32_e32 v64, v0
	v_mov_b32_e32 v65, v0
	v_mov_b32_e32 v66, v0
	v_mov_b32_e32 v67, v0
	v_mov_b32_e32 v68, v0
	v_mov_b32_e32 v69, v0
	v_mov_b32_e32 v70, v0
	v_mov_b32_e32 v71, v0
	v_mov_b32_e32 v72, v0
	v_mov_b32_e32 v73, v0
	v_mov_b32_e32 v74, v0
	v_mov_b32_e32 v75, v0
	v_mov_b32_e32 v76, v0
	v_mov_b32_e32 v77, v0
	v_mov_b32_e32 v78, v0
	v_mov_b32_e32 v79, v0
	v_mov_b32_e32 v88, v0
	v_mov_b32_e32 v89, v0
	v_mov_b32_e32 v90, v0
	v_mov_b32_e32 v91, v0
	v_mov_b32_e32 v92, v0
	v_mov_b32_e32 v93, v0
	v_mov_b32_e32 v94, v0
	v_mov_b32_e32 v95, v0
	v_mov_b32_e32 v104, v0
	v_mov_b32_e32 v105, v0
	v_mov_b32_e32 v106, v0
	v_mov_b32_e32 v107, v0
	v_mov_b32_e32 v108, v0
	v_mov_b32_e32 v109, v0
	v_mov_b32_e32 v110, v0
	v_mov_b32_e32 v111, v0
	v_mov_b32_e32 v80, v0
	v_mov_b32_e32 v81, v0
	v_mov_b32_e32 v82, v0
	v_mov_b32_e32 v83, v0
	v_mov_b32_e32 v84, v0
	v_mov_b32_e32 v85, v0
	v_mov_b32_e32 v86, v0
	v_mov_b32_e32 v87, v0
	v_mov_b32_e32 v96, v0
	v_mov_b32_e32 v97, v0
	v_mov_b32_e32 v98, v0
	v_mov_b32_e32 v99, v0
	v_mov_b32_e32 v100, v0
	v_mov_b32_e32 v101, v0
	v_mov_b32_e32 v102, v0
	v_mov_b32_e32 v103, v0
	v_mov_b32_e32 v112, v0
	v_mov_b32_e32 v113, v0
	v_mov_b32_e32 v114, v0
	v_mov_b32_e32 v115, v0
	v_mov_b32_e32 v116, v0
	v_mov_b32_e32 v117, v0
	v_mov_b32_e32 v118, v0
	v_mov_b32_e32 v119, v0
	v_mov_b32_e32 v120, v0
	v_mov_b32_e32 v121, v0
	v_mov_b32_e32 v122, v0
	v_mov_b32_e32 v123, v0
	v_mov_b32_e32 v124, v0
	v_mov_b32_e32 v125, v0
	v_mov_b32_e32 v126, v0
	v_mov_b32_e32 v127, v0
	.p2align	6

; #define ATT_LAS __attribute__((address_space(3)))
; __device__ __forceinline__ unsigned cvtpk_s(float lo, float hi) { f32x2_t v = {lo, hi}; bf16x2_t b = __builtin_convertvector(v, bf16x2_t); return __builtin_bit_cast(unsigned, b); }
; #define ATT_SBAR() __builtin_amdgcn_sched_barrier(0)
; #define ATT_VLOAD(dst, d0) do { _Pragma("unroll") for (int ks = 0; ks < 4; ++ks) { dst[2 * ks] = vtr(vp + (d0) * 4096 + ks * 1024); dst[2 * ks + 1] = vtr(vp + (d0) * 4096 + ks * 1024 + 512); } } while (0)
; __device__ __forceinline__ void attn_unit(const int b, const int h, const int qb, const bf16_t* Q, const bf16_t* K, const bf16_t* V, bf16_t* O, ATT_LAS char* shm, const float lam) {
;     ...
;             for (int d0 = 0; d0 < 4; ++d0) { kf[2 * d0] = *(const ATT_LAS bf16x8*)(kp + d0 * 2048); kf[2 * d0 + 1] = *(const ATT_LAS bf16x8*)(kp + d0 * 2048 + 512); }
;             ATT_VLOAD(va, 0);
;             ATT_SBAR();
;             f32x16 p0 = f32x16{}, p1 = f32x16{};
; #pragma unroll
;             for (int d0 = 0; d0 < 4; ++d0) { p0 = __builtin_amdgcn_mfma_f32_32x32x16_bf16(kf[2 * d0], qr[d0], p0, 0, 0, 0); p1 = __builtin_amdgcn_mfma_f32_32x32x16_bf16(kf[2 * d0 + 1], qr[d0], p1, 0, 0, 0); }
;             ATT_SBAR();
;             ATT_VLOAD(vb, 1);
;             ATT_SBAR();
; #pragma unroll
;             for (int r = 0; r < 16; ++r) { p0[r] = __builtin_amdgcn_exp2f(p0[r]); p1[r] = __builtin_amdgcn_exp2f(p1[r]); }
;             u32x4 pw[4];
; #pragma unroll
;             for (int j = 0; j < 4; ++j) { pw[0][j] = cvtpk_s(p0[2 * j], p0[2 * j + 1]); pw[1][j] = cvtpk_s(p0[8 + 2 * j], p0[9 + 2 * j]); pw[2][j] = cvtpk_s(p1[2 * j], p1[2 * j + 1]); pw[3][j] = cvtpk_s(p1[8 + 2 * j], p1[9 + 2 * j]); }
;             { float sa = 0.f, sb = 0.f;
; #pragma unroll
;               for (int r = 0; r < 16; ++r) { sa += p0[r]; sb += p1[r]; }
;               l_reg += sa + sb; }
.Latt_nok2:
	s_nop 1
	v_readfirstlane_b32 s100, v140
	v_readfirstlane_b32 s101, v141
	s_nop 1
	s_bfe_u32 s36, s3, 0x10006
	s_lshl_b32 s36, s36, 6
	s_sub_u32 s100, s100, s36
	s_subb_u32 s101, s101, 0
	v_subrev_u32_e32 v140, s100, v140
	v_subrev_u32_e32 v142, s100, v142
	s_and_b32 s98, s42, 1
	s_barrier
	v_add_u32_e32 v0, 0, v123
	v_xor_b32_e32 v162, 32, v0
	v_xor_b32_e32 v163, 64, v0
	v_xor_b32_e32 v141, 0x60, v0
	ds_read_b128 v[232:235], v0
	ds_read_b128 v[236:239], v162
	ds_read_b128 v[240:243], v163
	ds_read_b128 v[244:247], v141
	s_waitcnt lgkmcnt(3)
	v_mfma_f32_32x32x16_bf16 v[66:81], v[232:235], v[110:113], 0
	ds_read_b128 v[232:235], v0 offset:4096
	s_waitcnt lgkmcnt(3)
	v_mfma_f32_32x32x16_bf16 v[66:81], v[236:239], v[106:109], v[66:81]
	ds_read_b128 v[236:239], v162 offset:4096
	s_waitcnt lgkmcnt(3)
	v_mfma_f32_32x32x16_bf16 v[66:81], v[240:243], v[102:105], v[66:81]
	ds_read_b128 v[240:243], v163 offset:4096
	s_waitcnt lgkmcnt(3)
	v_mfma_f32_32x32x16_bf16 v[66:81], v[244:247], v[98:101], v[66:81]
	ds_read_b128 v[244:247], v141 offset:4096
	s_waitcnt lgkmcnt(3)
	v_mfma_f32_32x32x16_bf16 v[82:97], v[232:235], v[110:113], 0
	s_waitcnt lgkmcnt(2)
	v_mfma_f32_32x32x16_bf16 v[82:97], v[236:239], v[106:109], v[82:97]
	s_waitcnt lgkmcnt(1)
	v_mfma_f32_32x32x16_bf16 v[82:97], v[240:243], v[102:105], v[82:97]
	s_waitcnt lgkmcnt(0)
	v_mfma_f32_32x32x16_bf16 v[82:97], v[244:247], v[98:101], v[82:97]
	s_nop 15
	v_exp_f32_e32 v66, v66
	v_exp_f32_e32 v67, v67
	v_exp_f32_e32 v68, v68
	v_exp_f32_e32 v69, v69
	v_exp_f32_e32 v70, v70
	v_exp_f32_e32 v71, v71
	v_exp_f32_e32 v72, v72
	v_exp_f32_e32 v73, v73
	v_exp_f32_e32 v74, v74
	v_exp_f32_e32 v75, v75
	v_exp_f32_e32 v76, v76
	v_exp_f32_e32 v77, v77
	v_exp_f32_e32 v78, v78
	v_exp_f32_e32 v79, v79
	v_exp_f32_e32 v80, v80
	v_exp_f32_e32 v81, v81
	v_exp_f32_e32 v82, v82
	v_exp_f32_e32 v83, v83
	v_exp_f32_e32 v84, v84
	v_exp_f32_e32 v85, v85
	v_exp_f32_e32 v86, v86
	v_exp_f32_e32 v87, v87
	v_exp_f32_e32 v88, v88
	v_exp_f32_e32 v89, v89
	v_exp_f32_e32 v90, v90
	v_exp_f32_e32 v91, v91
	v_exp_f32_e32 v92, v92
	v_exp_f32_e32 v93, v93
	v_exp_f32_e32 v94, v94
	v_exp_f32_e32 v95, v95
	v_exp_f32_e32 v96, v96
	v_exp_f32_e32 v97, v97
	v_add_f32_e32 v252, v66, v67
	v_add_f32_e32 v252, v252, v68
	v_add_f32_e32 v252, v252, v69
	v_add_f32_e32 v252, v252, v70
	v_add_f32_e32 v252, v252, v71
	v_add_f32_e32 v252, v252, v72
	v_add_f32_e32 v252, v252, v73
	v_add_f32_e32 v252, v252, v74
	v_add_f32_e32 v252, v252, v75
	v_add_f32_e32 v252, v252, v76
	v_add_f32_e32 v252, v252, v77
	v_add_f32_e32 v252, v252, v78
	v_add_f32_e32 v252, v252, v79
	v_add_f32_e32 v252, v252, v80
	v_add_f32_e32 v252, v252, v81
	v_add_f32_e32 v253, v82, v83
	v_add_f32_e32 v253, v253, v84
	v_add_f32_e32 v253, v253, v85
	v_add_f32_e32 v253, v253, v86
	v_add_f32_e32 v253, v253, v87
	v_add_f32_e32 v253, v253, v88
	v_add_f32_e32 v253, v253, v89
	v_add_f32_e32 v253, v253, v90
	v_add_f32_e32 v253, v253, v91
	v_add_f32_e32 v253, v253, v92
	v_add_f32_e32 v253, v253, v93
	v_add_f32_e32 v253, v253, v94
	v_add_f32_e32 v253, v253, v95
	v_add_f32_e32 v253, v253, v96
	v_add_f32_e32 v253, v253, v97
	s_cmp_lt_u32 s43, 3
	s_cbranch_scc1 .Latt_tail
	.p2align	6

;     __host__ __device__ bool next(int i, Unit& u) const { if (!so.next(i >> 1, u)) return false; u.seg = i & 1; return true; }
; template <class Epi, class Sched, bool ALIGN_EPI = false, bool SP2 = false>
; __device__ __forceinline__ void gemm_phase(PG8_LAS unsigned char* lds, const Gemm g, const Sched& S, const Epi& E) {
;     ...
;         const bool has_next = S.next(ui + 1, nxt);
;         const char* nA = has_next ? (const char*)(nxt.seg ? g.A1 : g.A0) + (size_t)nxt.pm * tstep : cA; const char* nB = has_next ? (const char*)(nxt.seg ? g.B1 : g.B0) + (size_t)nxt.pn * tstep : cB;
.LBB0_572:
	s_ashr_i32 s39, s38, 31
	s_lshl_b64 s[42:43], s[38:39], 18
	s_cmp_eq_u32 s81, 0
	s_cselect_b32 s39, s8, s54
	s_cselect_b32 s31, s9, s55
	s_cselect_b32 s47, s68, s70
	s_cselect_b32 s52, s69, s71
	s_add_u32 s42, s39, s42
	s_addc_u32 s43, s31, s43
	s_and_b64 s[44:45], s[4:5], exec
	s_cselect_b32 s31, s43, s49
	s_cselect_b32 s39, s42, s48
	s_ashr_i32 s41, s40, 31
	s_lshl_b64 s[44:45], s[40:41], 18
	s_add_u32 s44, s47, s44
	s_addc_u32 s45, s52, s45
	s_and_b64 s[52:53], s[4:5], exec
	s_cselect_b32 s41, s45, s51
	s_cselect_b32 s47, s44, s50
	s_add_u32 s48, s48, 0x20080
	s_addc_u32 s49, s49, 0
	s_add_u32 s82, s50, 0x100
	s_addc_u32 s83, s51, 0
	s_mov_b32 s84, -2
	.p2align	6

;     __host__ __device__ bool next(int i, Unit& u) const { if (!so.next(i >> 1, u)) return false; u.seg = i & 1; return true; }
; template <class Epi, class Sched, bool ALIGN_EPI = false, bool SP2 = false>
; __device__ __forceinline__ void gemm_phase(PG8_LAS unsigned char* lds, const Gemm g, const Sched& S, const Epi& E) {
;     ...
;         const bool has_next = S.next(ui + 1, nxt);
;         const char* nA = has_next ? (const char*)(nxt.seg ? g.A1 : g.A0) + (size_t)nxt.pm * tstep : cA; const char* nB = has_next ? (const char*)(nxt.seg ? g.B1 : g.B0) + (size_t)nxt.pn * tstep : cB;
;     ...
;         if (!(Epi::KEEP && cur.seg == 0)) {
; #pragma unroll
;         for (int a = 0; a < 2; ++a)
; #pragma unroll
;             for (int b = 0; b < 2; ++b)
; #pragma unroll
;                 for (int m = 0; m < 4; ++m)
; #pragma unroll
;                     for (int n = 0; n < 2; ++n) acc[a][b][m][n] = (f32x4){0.f, 0.f, 0.f, 0.f};
;         }
;         cur = nxt; cA = nA; cB = nB; ++ui;
.LBB0_679:
	s_ashr_i32 s37, s36, 31
	s_lshl_b64 s[30:31], s[36:37], 19
	s_add_u32 s40, s56, s30
	s_addc_u32 s41, s57, s31
	s_and_b64 s[30:31], s[4:5], exec
	s_cselect_b32 s37, s41, s47
	s_cselect_b32 s72, s40, s46
	s_ashr_i32 s39, s38, 31
	s_lshl_b64 s[30:31], s[38:39], 19
	s_add_u32 s42, s64, s30
	s_addc_u32 s43, s65, s31
	s_and_b64 s[30:31], s[4:5], exec
	s_cselect_b32 s39, s43, s49
	s_cselect_b32 s73, s42, s48
	s_add_u32 s46, s46, 0x40080
	s_addc_u32 s47, s47, 0
	s_add_u32 s74, s48, 0x100
	v_mov_b32_e32 v0, 0
	s_addc_u32 s3, s49, 0
	s_mov_b32 s30, -2
	v_mov_b32_e32 v1, v0
	v_mov_b32_e32 v2, v0
	s_waitcnt lgkmcnt(0)
	v_mov_b32_e32 v3, v0
	v_mov_b32_e32 v4, v0
	v_mov_b32_e32 v5, v0
	v_mov_b32_e32 v6, v0
	v_mov_b32_e32 v7, v0
	v_mov_b32_e32 v12, v0
	v_mov_b32_e32 v13, v0
	v_mov_b32_e32 v14, v0
	v_mov_b32_e32 v15, v0
	v_mov_b32_e32 v20, v0
	v_mov_b32_e32 v21, v0
	v_mov_b32_e32 v22, v0
	v_mov_b32_e32 v23, v0
	v_mov_b32_e32 v32, v0
	v_mov_b32_e32 v33, v0
	v_mov_b32_e32 v34, v0
	v_mov_b32_e32 v35, v0
	v_mov_b32_e32 v36, v0
	v_mov_b32_e32 v37, v0
	v_mov_b32_e32 v38, v0
	v_mov_b32_e32 v39, v0
	v_mov_b32_e32 v48, v0
	v_mov_b32_e32 v49, v0
	v_mov_b32_e32 v50, v0
	v_mov_b32_e32 v51, v0
	v_mov_b32_e32 v52, v0
	v_mov_b32_e32 v53, v0
	v_mov_b32_e32 v54, v0
	v_mov_b32_e32 v55, v0
	v_mov_b32_e32 v8, v0
	v_mov_b32_e32 v9, v0
	v_mov_b32_e32 v10, v0
	v_mov_b32_e32 v11, v0
	v_mov_b32_e32 v16, v0
	v_mov_b32_e32 v17, v0
	v_mov_b32_e32 v18, v0
	v_mov_b32_e32 v19, v0
	v_mov_b32_e32 v24, v0
	v_mov_b32_e32 v25, v0
	v_mov_b32_e32 v26, v0
	v_mov_b32_e32 v27, v0
	v_mov_b32_e32 v28, v0
	v_mov_b32_e32 v29, v0
	v_mov_b32_e32 v30, v0
	v_mov_b32_e32 v31, v0
	v_mov_b32_e32 v40, v0
	v_mov_b32_e32 v41, v0
	v_mov_b32_e32 v42, v0
	v_mov_b32_e32 v43, v0
	v_mov_b32_e32 v44, v0
	v_mov_b32_e32 v45, v0
	v_mov_b32_e32 v46, v0
	v_mov_b32_e32 v47, v0
	v_mov_b32_e32 v56, v0
	v_mov_b32_e32 v57, v0
	v_mov_b32_e32 v58, v0
	v_mov_b32_e32 v59, v0
	v_mov_b32_e32 v60, v0
	v_mov_b32_e32 v61, v0
	v_mov_b32_e32 v62, v0
	v_mov_b32_e32 v63, v0
	v_mov_b32_e32 v64, v0
	v_mov_b32_e32 v65, v0
	v_mov_b32_e32 v66, v0
	v_mov_b32_e32 v67, v0
	v_mov_b32_e32 v68, v0
	v_mov_b32_e32 v69, v0
	v_mov_b32_e32 v70, v0
	v_mov_b32_e32 v71, v0
	v_mov_b32_e32 v80, v0
	v_mov_b32_e32 v81, v0
	v_mov_b32_e32 v82, v0
	v_mov_b32_e32 v83, v0
	v_mov_b32_e32 v84, v0
	v_mov_b32_e32 v85, v0
	v_mov_b32_e32 v86, v0
	v_mov_b32_e32 v87, v0
	v_mov_b32_e32 v96, v0
	v_mov_b32_e32 v97, v0
	v_mov_b32_e32 v98, v0
	v_mov_b32_e32 v99, v0
	v_mov_b32_e32 v100, v0
	v_mov_b32_e32 v101, v0
	v_mov_b32_e32 v102, v0
	v_mov_b32_e32 v103, v0
	v_mov_b32_e32 v112, v0
	v_mov_b32_e32 v113, v0
	v_mov_b32_e32 v114, v0
	v_mov_b32_e32 v115, v0
	v_mov_b32_e32 v116, v0
	v_mov_b32_e32 v117, v0
	v_mov_b32_e32 v118, v0
	v_mov_b32_e32 v119, v0
	v_mov_b32_e32 v72, v0
	v_mov_b32_e32 v73, v0
	v_mov_b32_e32 v74, v0
	v_mov_b32_e32 v75, v0
	v_mov_b32_e32 v76, v0
	v_mov_b32_e32 v77, v0
	v_mov_b32_e32 v78, v0
	v_mov_b32_e32 v79, v0
	v_mov_b32_e32 v88, v0
	v_mov_b32_e32 v89, v0
	v_mov_b32_e32 v90, v0
	v_mov_b32_e32 v91, v0
	v_mov_b32_e32 v92, v0
	v_mov_b32_e32 v93, v0
	v_mov_b32_e32 v94, v0
	v_mov_b32_e32 v95, v0
	v_mov_b32_e32 v104, v0
	v_mov_b32_e32 v105, v0
	v_mov_b32_e32 v106, v0
	v_mov_b32_e32 v107, v0
	v_mov_b32_e32 v108, v0
	v_mov_b32_e32 v109, v0
	v_mov_b32_e32 v110, v0
	v_mov_b32_e32 v111, v0
	v_mov_b32_e32 v120, v0
	v_mov_b32_e32 v121, v0
	v_mov_b32_e32 v122, v0
	v_mov_b32_e32 v123, v0
	v_mov_b32_e32 v124, v0
	v_mov_b32_e32 v125, v0
	v_mov_b32_e32 v126, v0
	v_mov_b32_e32 v127, v0
	.p2align	6

;     __host__ __device__ bool next(int i, Unit& u) const { if (!so.next(i >> 1, u)) return false; u.seg = i & 1; return true; }
; template <class Epi, class Sched, bool ALIGN_EPI = false, bool SP2 = false>
; __device__ __forceinline__ void gemm_phase(PG8_LAS unsigned char* lds, const Gemm g, const Sched& S, const Epi& E) {
;     ...
;         const bool has_next = S.next(ui + 1, nxt);
;         const char* nA = has_next ? (const char*)(nxt.seg ? g.A1 : g.A0) + (size_t)nxt.pm * tstep : cA; const char* nB = has_next ? (const char*)(nxt.seg ? g.B1 : g.B0) + (size_t)nxt.pn * tstep : cB;
;     ...
;         if (!(Epi::KEEP && cur.seg == 0)) {
; #pragma unroll
;         for (int a = 0; a < 2; ++a)
; #pragma unroll
;             for (int b = 0; b < 2; ++b)
; #pragma unroll
;                 for (int m = 0; m < 4; ++m)
; #pragma unroll
;                     for (int n = 0; n < 2; ++n) acc[a][b][m][n] = (f32x4){0.f, 0.f, 0.f, 0.f};
;         }
;         cur = nxt; cA = nA; cB = nB; ++ui;
.LBB0_770:
	s_ashr_i32 s21, s20, 31
	s_lshl_b64 s[24:25], s[20:21], 19
	s_add_u32 s24, s10, s24
	s_addc_u32 s25, s11, s25
	s_and_b64 s[26:27], s[4:5], exec
	s_cselect_b32 s21, s25, s39
	s_cselect_b32 s53, s24, s38
	s_ashr_i32 s23, s22, 31
	s_lshl_b64 s[26:27], s[22:23], 19
	s_add_u32 s26, s60, s26
	s_addc_u32 s27, s61, s27
	s_and_b64 s[30:31], s[4:5], exec
	s_cselect_b32 s23, s27, s41
	s_cselect_b32 s54, s26, s40
	s_add_u32 s38, s38, 0x40080
	s_addc_u32 s39, s39, 0
	s_add_u32 s55, s40, 0x100
	v_mov_b32_e32 v0, 0
	s_addc_u32 s3, s41, 0
	s_mov_b32 s30, -2
	v_mov_b32_e32 v1, v0
	v_mov_b32_e32 v2, v0
	v_mov_b32_e32 v3, v0
	v_mov_b32_e32 v4, v0
	v_mov_b32_e32 v5, v0
	v_mov_b32_e32 v6, v0
	v_mov_b32_e32 v7, v0
	v_mov_b32_e32 v16, v0
	v_mov_b32_e32 v17, v0
	v_mov_b32_e32 v18, v0
	v_mov_b32_e32 v19, v0
	v_mov_b32_e32 v20, v0
	v_mov_b32_e32 v21, v0
	v_mov_b32_e32 v22, v0
	v_mov_b32_e32 v23, v0
	v_mov_b32_e32 v32, v0
	v_mov_b32_e32 v33, v0
	v_mov_b32_e32 v34, v0
	v_mov_b32_e32 v35, v0
	v_mov_b32_e32 v36, v0
	v_mov_b32_e32 v37, v0
	v_mov_b32_e32 v38, v0
	v_mov_b32_e32 v39, v0
	v_mov_b32_e32 v48, v0
	v_mov_b32_e32 v49, v0
	v_mov_b32_e32 v50, v0
	v_mov_b32_e32 v51, v0
	v_mov_b32_e32 v52, v0
	v_mov_b32_e32 v53, v0
	v_mov_b32_e32 v54, v0
	v_mov_b32_e32 v55, v0
	v_mov_b32_e32 v8, v0
	v_mov_b32_e32 v9, v0
	v_mov_b32_e32 v10, v0
	v_mov_b32_e32 v11, v0
	v_mov_b32_e32 v12, v0
	v_mov_b32_e32 v13, v0
	v_mov_b32_e32 v14, v0
	v_mov_b32_e32 v15, v0
	v_mov_b32_e32 v24, v0
	v_mov_b32_e32 v25, v0
	v_mov_b32_e32 v26, v0
	v_mov_b32_e32 v27, v0
	v_mov_b32_e32 v28, v0
	v_mov_b32_e32 v29, v0
	v_mov_b32_e32 v30, v0
	v_mov_b32_e32 v31, v0
	v_mov_b32_e32 v40, v0
	v_mov_b32_e32 v41, v0
	v_mov_b32_e32 v42, v0
	v_mov_b32_e32 v43, v0
	v_mov_b32_e32 v44, v0
	v_mov_b32_e32 v45, v0
	v_mov_b32_e32 v46, v0
	v_mov_b32_e32 v47, v0
	v_mov_b32_e32 v56, v0
	v_mov_b32_e32 v57, v0
	v_mov_b32_e32 v58, v0
	v_mov_b32_e32 v59, v0
	v_mov_b32_e32 v60, v0
	v_mov_b32_e32 v61, v0
	v_mov_b32_e32 v62, v0
	v_mov_b32_e32 v63, v0
	v_mov_b32_e32 v64, v0
	v_mov_b32_e32 v65, v0
	v_mov_b32_e32 v66, v0
	v_mov_b32_e32 v67, v0
	v_mov_b32_e32 v68, v0
	v_mov_b32_e32 v69, v0
	v_mov_b32_e32 v70, v0
	v_mov_b32_e32 v71, v0
	v_mov_b32_e32 v80, v0
	v_mov_b32_e32 v81, v0
	v_mov_b32_e32 v82, v0
	v_mov_b32_e32 v83, v0
	v_mov_b32_e32 v84, v0
	v_mov_b32_e32 v85, v0
	v_mov_b32_e32 v86, v0
	v_mov_b32_e32 v87, v0
	v_mov_b32_e32 v96, v0
	v_mov_b32_e32 v97, v0
	v_mov_b32_e32 v98, v0
	v_mov_b32_e32 v99, v0
	v_mov_b32_e32 v100, v0
	v_mov_b32_e32 v101, v0
	v_mov_b32_e32 v102, v0
	v_mov_b32_e32 v103, v0
	v_mov_b32_e32 v108, v0
	v_mov_b32_e32 v109, v0
	v_mov_b32_e32 v110, v0
	v_mov_b32_e32 v111, v0
	v_mov_b32_e32 v112, v0
	v_mov_b32_e32 v113, v0
	v_mov_b32_e32 v114, v0
	v_mov_b32_e32 v115, v0
	v_mov_b32_e32 v72, v0
	v_mov_b32_e32 v73, v0
	v_mov_b32_e32 v74, v0
	v_mov_b32_e32 v75, v0
	v_mov_b32_e32 v76, v0
	v_mov_b32_e32 v77, v0
	v_mov_b32_e32 v78, v0
	v_mov_b32_e32 v79, v0
	v_mov_b32_e32 v88, v0
	v_mov_b32_e32 v89, v0
	v_mov_b32_e32 v90, v0
	v_mov_b32_e32 v91, v0
	v_mov_b32_e32 v92, v0
	v_mov_b32_e32 v93, v0
	v_mov_b32_e32 v94, v0
	v_mov_b32_e32 v95, v0
	v_mov_b32_e32 v104, v0
	v_mov_b32_e32 v105, v0
	v_mov_b32_e32 v106, v0
	v_mov_b32_e32 v107, v0
	v_mov_b32_e32 v116, v0
	v_mov_b32_e32 v117, v0
	v_mov_b32_e32 v118, v0
	v_mov_b32_e32 v119, v0
	v_mov_b32_e32 v120, v0
	v_mov_b32_e32 v121, v0
	v_mov_b32_e32 v122, v0
	v_mov_b32_e32 v123, v0
	v_mov_b32_e32 v124, v0
	v_mov_b32_e32 v125, v0
	v_mov_b32_e32 v126, v0
	v_mov_b32_e32 v127, v0
	.p2align	6

; template <class Epi, class Sched, bool ALIGN_EPI = false, bool SP2 = false>
; __device__ __forceinline__ void gemm_phase(PG8_LAS unsigned char* lds, const Gemm g, const Sched& S, const Epi& E) {
;     ...
;         const char* nA = has_next ? (const char*)(nxt.seg ? g.A1 : g.A0) + (size_t)nxt.pm * tstep : cA; const char* nB = has_next ? (const char*)(nxt.seg ? g.B1 : g.B0) + (size_t)nxt.pn * tstep : cB;
;         for (int t = 0; t < nt; t += 2) {
;             const bool last = (t == nt - 2);
;             const char* a1 = cA + (size_t)(t + 1) * kstep;
;             const char* a2 = last ? nA : cA + (size_t)(t + 2) * kstep; const char* b2 = last ? nB : cB + (size_t)(t + 2) * kstep;
;             const char* a3 = a2 + kstep; const char* b3 = b2 + kstep;
;     ...
;         if (!(Epi::KEEP && cur.seg == 0)) {
; #pragma unroll
;         for (int a = 0; a < 2; ++a)
; #pragma unroll
;             for (int b = 0; b < 2; ++b)
; #pragma unroll
;                 for (int m = 0; m < 4; ++m)
; #pragma unroll
;                     for (int n = 0; n < 2; ++n) acc[a][b][m][n] = (f32x4){0.f, 0.f, 0.f, 0.f};
;         }
;         cur = nxt; cA = nA; cB = nB; ++ui;
.LBB0_875:
	s_add_u32 s34, s34, 0xb0080
	s_addc_u32 s35, s35, 0
	s_add_u32 s53, s36, 0x100
	v_mov_b32_e32 v0, 0
	s_addc_u32 s54, s37, 0
	s_mov_b32 s30, -2
	v_mov_b32_e32 v1, v0
	v_mov_b32_e32 v2, v0
	v_mov_b32_e32 v3, v0
	v_mov_b32_e32 v4, v0
	v_mov_b32_e32 v5, v0
	v_mov_b32_e32 v6, v0
	v_mov_b32_e32 v7, v0
	v_mov_b32_e32 v12, v0
	v_mov_b32_e32 v13, v0
	v_mov_b32_e32 v14, v0
	v_mov_b32_e32 v15, v0
	v_mov_b32_e32 v20, v0
	v_mov_b32_e32 v21, v0
	v_mov_b32_e32 v22, v0
	v_mov_b32_e32 v23, v0
	v_mov_b32_e32 v28, v0
	v_mov_b32_e32 v29, v0
	v_mov_b32_e32 v30, v0
	v_mov_b32_e32 v31, v0
	v_mov_b32_e32 v36, v0
	v_mov_b32_e32 v37, v0
	v_mov_b32_e32 v38, v0
	v_mov_b32_e32 v39, v0
	v_mov_b32_e32 v44, v0
	v_mov_b32_e32 v45, v0
	v_mov_b32_e32 v46, v0
	v_mov_b32_e32 v47, v0
	v_mov_b32_e32 v52, v0
	v_mov_b32_e32 v53, v0
	v_mov_b32_e32 v54, v0
	v_mov_b32_e32 v55, v0
	v_mov_b32_e32 v8, v0
	v_mov_b32_e32 v9, v0
	v_mov_b32_e32 v10, v0
	v_mov_b32_e32 v11, v0
	v_mov_b32_e32 v16, v0
	v_mov_b32_e32 v17, v0
	v_mov_b32_e32 v18, v0
	v_mov_b32_e32 v19, v0
	v_mov_b32_e32 v24, v0
	v_mov_b32_e32 v25, v0
	v_mov_b32_e32 v26, v0
	v_mov_b32_e32 v27, v0
	v_mov_b32_e32 v32, v0
	v_mov_b32_e32 v33, v0
	v_mov_b32_e32 v34, v0
	v_mov_b32_e32 v35, v0
	v_mov_b32_e32 v40, v0
	v_mov_b32_e32 v41, v0
	v_mov_b32_e32 v42, v0
	v_mov_b32_e32 v43, v0
	v_mov_b32_e32 v48, v0
	v_mov_b32_e32 v49, v0
	v_mov_b32_e32 v50, v0
	v_mov_b32_e32 v51, v0
	v_mov_b32_e32 v56, v0
	v_mov_b32_e32 v57, v0
	v_mov_b32_e32 v58, v0
	v_mov_b32_e32 v59, v0
	v_mov_b32_e32 v60, v0
	v_mov_b32_e32 v61, v0
	v_mov_b32_e32 v62, v0
	v_mov_b32_e32 v63, v0
	v_mov_b32_e32 v64, v0
	v_mov_b32_e32 v65, v0
	v_mov_b32_e32 v66, v0
	v_mov_b32_e32 v67, v0
	v_mov_b32_e32 v68, v0
	v_mov_b32_e32 v69, v0
	v_mov_b32_e32 v70, v0
	v_mov_b32_e32 v71, v0
	v_mov_b32_e32 v76, v0
	v_mov_b32_e32 v77, v0
	v_mov_b32_e32 v78, v0
	v_mov_b32_e32 v79, v0
	v_mov_b32_e32 v84, v0
	v_mov_b32_e32 v85, v0
	v_mov_b32_e32 v86, v0
	v_mov_b32_e32 v87, v0
	v_mov_b32_e32 v92, v0
	v_mov_b32_e32 v93, v0
	v_mov_b32_e32 v94, v0
	v_mov_b32_e32 v95, v0
	v_mov_b32_e32 v100, v0
	v_mov_b32_e32 v101, v0
	v_mov_b32_e32 v102, v0
	v_mov_b32_e32 v103, v0
	v_mov_b32_e32 v108, v0
	v_mov_b32_e32 v109, v0
	v_mov_b32_e32 v110, v0
	v_mov_b32_e32 v111, v0
	v_mov_b32_e32 v116, v0
	v_mov_b32_e32 v117, v0
	v_mov_b32_e32 v118, v0
	v_mov_b32_e32 v119, v0
	v_mov_b32_e32 v72, v0
	v_mov_b32_e32 v73, v0
	v_mov_b32_e32 v74, v0
	v_mov_b32_e32 v75, v0
	v_mov_b32_e32 v80, v0
	v_mov_b32_e32 v81, v0
	v_mov_b32_e32 v82, v0
	v_mov_b32_e32 v83, v0
	v_mov_b32_e32 v88, v0
	v_mov_b32_e32 v89, v0
	v_mov_b32_e32 v90, v0
	v_mov_b32_e32 v91, v0
	v_mov_b32_e32 v96, v0
	v_mov_b32_e32 v97, v0
	v_mov_b32_e32 v98, v0
	v_mov_b32_e32 v99, v0
	v_mov_b32_e32 v104, v0
	v_mov_b32_e32 v105, v0
	v_mov_b32_e32 v106, v0
	v_mov_b32_e32 v107, v0
	v_mov_b32_e32 v112, v0
	v_mov_b32_e32 v113, v0
	v_mov_b32_e32 v114, v0
	v_mov_b32_e32 v115, v0
	v_mov_b32_e32 v120, v0
	v_mov_b32_e32 v121, v0
	v_mov_b32_e32 v122, v0
	v_mov_b32_e32 v123, v0
	v_mov_b32_e32 v124, v0
	v_mov_b32_e32 v125, v0
	v_mov_b32_e32 v126, v0
	v_mov_b32_e32 v127, v0
	.p2align	6
